# plus: attention K/V cache warm-up loads 3 tiles ahead; sample-step attention cached-key loop hand-written with chunk-ahead loads
# baseline (speedup 1.0000x reference)
; __device__ __forceinline__ void attn_prompt_unit(ArgsK& a, LAS unsigned char* lds, int b, int h, int qb, int tid, int wave, int lane) {
;     ...
;         const bool more = kt + 1 < NT;
;         if (kt + 2 < NT) { const size_t r = rowb + (kt + 2) * 64 + skey; kreg2 = *(const u32x4*)(KB + r * 512 + h * 64 + sch * 8); vreg2 = *(const u32x4*)(VB + r * 512 + h * 64 + sch * 8);
;             if (tid < 64) ckreg2 = CUM[(rowb + (kt + 2) * 64 + tid) * 8 + h] * LOG2E; }
;     ...
;         kreg = kreg2; vreg = vreg2; ckreg = ckreg2;
.LBB0_244:
	s_waitcnt vmcnt(3)
	v_mov_b64_e32 v[26:27], v[34:35]
	s_waitcnt vmcnt(2)
	v_mov_b64_e32 v[30:31], v[38:39]
	v_mov_b64_e32 v[28:29], v[36:37]
	v_mov_b64_e32 v[32:33], v[40:41]
	v_mul_f32_e32 v223, 0x3fb8aa3b, v224
	s_cmp_ge_u32 s35, s58
	s_cbranch_scc1 .LBB0_249
.LBB0_245:
	v_add_co_u32_e32 v38, vcc, 0x4080000, v128
	s_nop 1
	v_addc_co_u32_e32 v39, vcc, 0, v129, vcc
	v_lshl_add_u64 v[226:227], v[128:129], 0, s[36:37]
	v_lshl_add_u64 v[228:229], v[38:39], 0, s[36:37]
	v_lshl_add_u64 v[226:227], v[226:227], 0, s[36:37]
	v_lshl_add_u64 v[228:229], v[228:229], 0, s[36:37]
	v_lshl_add_u64 v[226:227], v[226:227], 0, s[36:37]
	v_lshl_add_u64 v[228:229], v[228:229], 0, s[36:37]
	global_load_dwordx4 v[34:37], v[128:129], off
	s_nop 0
	global_load_dwordx4 v[38:41], v[38:39], off
	s_and_saveexec_b64 s[14:15], s[40:41]
	s_cbranch_execz .LBB0_247
	global_load_dword v224, v[170:171], off
.LBB0_247:
	s_or_b64 exec, exec, s[14:15]
	global_load_dword v230, v[226:227], off
	global_load_dword v231, v[228:229], off
	s_sub_i32 s14, s64, 63
	s_cmp_gt_i32 s14, s59
	s_cbranch_scc0 .LBB0_250

; #define LAS __attribute__((address_space(3)))
; __device__ __forceinline__ void attn_prompt_unit(ArgsK& a, LAS unsigned char* lds, int b, int h, int qb, int tid, int wave, int lane) {
;     ...
;         if (more) { *(LAS u32x4*)(bufn + AT_K + skey * 144 + sch * 16) = kreg; *(LAS u32x4*)(bufn + AT_V + skey * 160 + sch * 16) = vreg; if (tid < 64) ((LAS float*)(bufn + AT_CK))[tid] = ckreg; }
.LBB0_253:
	s_bitcmp1_b32 s14, 0
	s_cselect_b32 s14, 0x4d00, 0
	s_add_i32 s65, s14, 0
	v_add3_u32 v0, s65, v117, v207
	s_waitcnt vmcnt(4)
	ds_write_b128 v0, v[26:29]
	v_add3_u32 v0, s65, v208, v207
	s_waitcnt vmcnt(4)
	ds_write_b128 v0, v[30:33] offset:9216
	s_and_saveexec_b64 s[14:15], s[40:41]
	v_lshl_add_u32 v0, v160, 2, s65
	ds_write_b32 v0, v223 offset:19456
	s_or_b64 exec, exec, s[14:15]

; #define LAS __attribute__((address_space(3)))
; #define MFMA16(a_, b_, c_) __builtin_amdgcn_mfma_f32_16x16x32_bf16((a_), (b_), (c_), 0, 0, 0)
; __device__ __forceinline__ void attn_prompt_unit(ArgsK& a, LAS unsigned char* lds, int b, int h, int qb, int tid, int wave, int lane) {
;     ...
;         const bool more = kt + 1 < NT;
;         if (kt + 2 < NT) { const size_t r = rowb + (kt + 2) * 64 + skey; kreg2 = *(const u32x4*)(KB + r * 512 + h * 64 + sch * 8); vreg2 = *(const u32x4*)(VB + r * 512 + h * 64 + sch * 8);
;             if (tid < 64) ckreg2 = CUM[(rowb + (kt + 2) * 64 + tid) * 8 + h] * LOG2E; }
;         if (kt * 64 <= qw + 31) {
;             const LAS float* CK = (const LAS float*)(bufc + AT_CK);
;             f32x4 st[4][2];
; #pragma unroll
;             for (int kb = 0; kb < 4; ++kb) { const bf16x8 k0 = *(const LAS bf16x8*)(bufc + AT_K + (kb * 16 + l15) * 144 + quad * 16), k1 = *(const LAS bf16x8*)(bufc + AT_K + (kb * 16 + l15) * 144 + 64 + quad * 16);
;                 const f32x4 ckv = *(const LAS f32x4*)(CK + kb * 16 + quad * 4);
; #pragma unroll
;                 for (int qq = 0; qq < 2; ++qq) { const f32x4 ci = (f32x4){cq[qq] - ckv[0], cq[qq] - ckv[1], cq[qq] - ckv[2], cq[qq] - ckv[3]};
;                     st[kb][qq] = MFMA16(k0, qf[qq][0], ci); st[kb][qq] = MFMA16(k1, qf[qq][1], st[kb][qq]); } }
;             if (kt * 64 + 63 > qw) {
; #pragma unroll
;                 for (int kb = 0; kb < 4; ++kb)
; #pragma unroll
;                     for (int qq = 0; qq < 2; ++qq)
; #pragma unroll
;                         for (int j = 0; j < 4; ++j) if (kt * 64 + kb * 16 + quad * 4 + j > qw + qq * 16 + l15) st[kb][qq][j] = -INFINITY; }
.LBB0_264:
	v_add_co_u32_e32 v38, vcc, 0x4080000, v138
	s_nop 1
	v_addc_co_u32_e32 v39, vcc, 0, v139, vcc
	v_lshl_add_u64 v[226:227], v[138:139], 0, s[36:37]
	v_lshl_add_u64 v[228:229], v[38:39], 0, s[36:37]
	v_lshl_add_u64 v[226:227], v[226:227], 0, s[36:37]
	v_lshl_add_u64 v[228:229], v[228:229], 0, s[36:37]
	v_lshl_add_u64 v[226:227], v[226:227], 0, s[36:37]
	v_lshl_add_u64 v[228:229], v[228:229], 0, s[36:37]
	global_load_dwordx4 v[34:37], v[138:139], off
	s_nop 0
	global_load_dwordx4 v[38:41], v[38:39], off
	s_and_saveexec_b64 s[14:15], s[40:41]
	s_cbranch_execz .LBB0_266
	global_load_dword v180, v[136:137], off
.LBB0_266:
	s_or_b64 exec, exec, s[14:15]
	global_load_dword v230, v[226:227], off
	global_load_dword v231, v[228:229], off
	s_cmp_gt_i32 s12, s60
	s_cbranch_scc1 .LBB0_270
	s_bitcmp1_b32 s18, 0
	s_cselect_b32 s14, 0x4d00, 0
	s_add_i32 s19, s14, 0
	v_add_u32_e32 v141, s19, v111
	v_add_u32_e32 v142, v141, v211
	ds_read_b128 v[74:77], v142
	ds_read_b128 v[78:81], v141 offset:19456
	ds_read_b128 v[82:85], v141 offset:19520
	ds_read_b128 v[86:89], v142 offset:64
	ds_read_b128 v[98:101], v142 offset:2304
	s_cmp_le_i32 s12, s61
	s_waitcnt lgkmcnt(3)
	v_sub_f32_e32 v93, v25, v81
	v_sub_f32_e32 v92, v24, v80
	v_sub_f32_e32 v91, v23, v79
	v_sub_f32_e32 v90, v20, v78
	v_sub_f32_e32 v81, v21, v81
	v_sub_f32_e32 v80, v22, v80
	v_sub_f32_e32 v79, v19, v79
	v_sub_f32_e32 v78, v18, v78
	v_mfma_f32_16x16x32_bf16 v[90:93], v[74:77], v[6:9], v[90:93]
	s_nop 0
	v_mfma_f32_16x16x32_bf16 v[74:77], v[74:77], v[14:17], v[78:81]
	s_waitcnt lgkmcnt(1)
	v_mfma_f32_16x16x32_bf16 v[78:81], v[86:89], v[10:13], v[74:77]
	v_mfma_f32_16x16x32_bf16 v[90:93], v[86:89], v[2:5], v[90:93]
	s_nop 4
	ds_read_b128 v[74:77], v142 offset:2368
	v_sub_f32_e32 v89, v25, v85
	v_sub_f32_e32 v88, v24, v84
	v_sub_f32_e32 v87, v23, v83
	v_sub_f32_e32 v86, v20, v82
	v_sub_f32_e32 v85, v21, v85
	v_sub_f32_e32 v84, v22, v84
	s_waitcnt lgkmcnt(1)
	v_mfma_f32_16x16x32_bf16 v[86:89], v[98:101], v[6:9], v[86:89]
	v_sub_f32_e32 v83, v19, v83
	v_sub_f32_e32 v82, v18, v82
	s_waitcnt lgkmcnt(0)
	v_mfma_f32_16x16x32_bf16 v[94:97], v[74:77], v[2:5], v[86:89]
	s_nop 3
	ds_read_b128 v[86:89], v142 offset:4608
	ds_read_b128 v[102:105], v141 offset:19584
	v_mfma_f32_16x16x32_bf16 v[82:85], v[98:101], v[14:17], v[82:85]
	s_waitcnt lgkmcnt(0)
	v_sub_f32_e32 v101, v25, v105
	v_sub_f32_e32 v100, v24, v104
	v_sub_f32_e32 v99, v23, v103
	v_sub_f32_e32 v98, v20, v102
	v_sub_f32_e32 v105, v21, v105
	v_sub_f32_e32 v104, v22, v104
	v_sub_f32_e32 v103, v19, v103
	v_sub_f32_e32 v102, v18, v102
	v_mfma_f32_16x16x32_bf16 v[98:101], v[86:89], v[6:9], v[98:101]
	s_nop 0
	v_mfma_f32_16x16x32_bf16 v[86:89], v[86:89], v[14:17], v[102:105]
	s_nop 2
	v_add_u32_e32 v102, v141, v212
	v_mfma_f32_16x16x32_bf16 v[74:77], v[74:77], v[10:13], v[82:85]
	s_nop 2
	ds_read_b128 v[82:85], v142 offset:4672
	ds_read_b128 v[142:145], v141 offset:19648
	ds_read_b128 v[162:165], v102
	s_waitcnt lgkmcnt(1)
	v_sub_f32_e32 v105, v25, v145
	v_mfma_f32_16x16x32_bf16 v[98:101], v[82:85], v[2:5], v[98:101]
	v_sub_f32_e32 v104, v24, v144
	v_sub_f32_e32 v103, v23, v143
	v_sub_f32_e32 v145, v21, v145
	v_mfma_f32_16x16x32_bf16 v[82:85], v[82:85], v[10:13], v[86:89]
	v_sub_f32_e32 v144, v22, v144
	v_sub_f32_e32 v143, v19, v143
	s_nop 0
	ds_read_b128 v[86:89], v102 offset:64
	v_sub_f32_e32 v102, v20, v142
	v_sub_f32_e32 v142, v18, v142
	s_waitcnt lgkmcnt(1)
	v_mfma_f32_16x16x32_bf16 v[102:105], v[162:165], v[6:9], v[102:105]
	v_mfma_f32_16x16x32_bf16 v[142:145], v[162:165], v[14:17], v[142:145]
	s_waitcnt lgkmcnt(0)
	v_mfma_f32_16x16x32_bf16 v[102:105], v[86:89], v[2:5], v[102:105]
	v_mfma_f32_16x16x32_bf16 v[86:89], v[86:89], v[10:13], v[142:145]
	s_cbranch_scc1 .LBB0_269
	v_add_u32_e32 v141, s12, v110
	v_cmp_gt_i32_e32 vcc, v141, v126
	s_nop 1
	v_mov_b32_e32 v142, s31
	v_cmp_lt_i32_e64 s[14:15], v141, v126
	v_cndmask_b32_e32 v142, v90, v142, vcc
	v_add_u32_e32 v143, 2, v141
	v_cndmask_b32_e64 v90, v142, v90, s[14:15]
	v_cndmask_b32_e64 v91, v199, v91, s[14:15]
	v_cmp_le_i32_e64 s[14:15], v143, v126
	v_add_u32_e32 v144, 3, v141
	v_mov_b32_e32 v142, s31
	v_cndmask_b32_e64 v92, v199, v92, s[14:15]
	v_cmp_le_i32_e64 s[14:15], v144, v126
	v_add_u32_e32 v145, 19, v141
	v_add_u32_e32 v146, 35, v141
	v_cndmask_b32_e64 v93, v199, v93, s[14:15]
	v_cmp_gt_i32_e64 s[14:15], v141, v215
	s_nop 1
	v_cndmask_b32_e64 v142, v78, v142, s[14:15]
	v_cmp_lt_i32_e64 s[14:15], v141, v215
	s_nop 1
	v_cndmask_b32_e64 v78, v142, v78, s[14:15]
	v_cndmask_b32_e64 v79, v199, v79, s[14:15]
	v_cmp_le_i32_e64 s[14:15], v143, v215
	v_add_u32_e32 v142, 16, v141
	v_add_u32_e32 v143, 17, v141
	v_cndmask_b32_e64 v80, v199, v80, s[14:15]
	v_cmp_le_i32_e64 s[14:15], v144, v215
	v_add_u32_e32 v144, 18, v141
	s_nop 0
	v_cndmask_b32_e64 v81, v199, v81, s[14:15]
	v_cmp_gt_i32_e64 s[14:15], v142, v126
	v_mov_b32_e32 v142, s31
	v_cndmask_b32_e32 v74, v74, v142, vcc
	v_cmp_le_i32_e32 vcc, v143, v215
	v_cndmask_b32_e64 v94, v94, v142, s[14:15]
	v_cmp_le_i32_e64 s[14:15], v143, v126
	v_cndmask_b32_e32 v75, v199, v75, vcc
	v_cmp_le_i32_e32 vcc, v144, v215
	v_add_u32_e32 v143, 32, v141
	v_cndmask_b32_e64 v95, v199, v95, s[14:15]
	v_cndmask_b32_e32 v76, v199, v76, vcc
	v_cmp_le_i32_e32 vcc, v145, v215
	v_cmp_le_i32_e64 s[14:15], v144, v126
	v_add_u32_e32 v144, 33, v141
	v_cndmask_b32_e32 v77, v199, v77, vcc
	v_cmp_gt_i32_e32 vcc, v143, v126
	v_cndmask_b32_e64 v96, v199, v96, s[14:15]
	v_cmp_le_i32_e64 s[14:15], v145, v126
	v_cndmask_b32_e32 v98, v98, v142, vcc
	v_cmp_le_i32_e32 vcc, v144, v126
	v_add_u32_e32 v145, 34, v141
	v_cndmask_b32_e64 v97, v199, v97, s[14:15]
	v_cndmask_b32_e32 v99, v199, v99, vcc
	v_cmp_le_i32_e32 vcc, v145, v126
	s_nop 1
	v_cndmask_b32_e32 v100, v199, v100, vcc
	v_cmp_le_i32_e32 vcc, v146, v126
	s_nop 1
	v_cndmask_b32_e32 v101, v199, v101, vcc
	v_cmp_gt_i32_e32 vcc, v143, v215
	v_add_u32_e32 v143, 48, v141
	s_nop 0
	v_cndmask_b32_e32 v82, v82, v142, vcc
	v_cmp_le_i32_e32 vcc, v144, v215
	v_add_u32_e32 v144, 49, v141
	s_nop 0
	v_cndmask_b32_e32 v83, v199, v83, vcc
	v_cmp_le_i32_e32 vcc, v145, v215
	v_add_u32_e32 v145, 50, v141
	v_add_u32_e32 v141, 51, v141
	v_cndmask_b32_e32 v84, v199, v84, vcc
	v_cmp_le_i32_e32 vcc, v146, v215
	s_nop 1
	v_cndmask_b32_e32 v85, v199, v85, vcc
	v_cmp_gt_i32_e32 vcc, v143, v126
	s_nop 1
	v_cndmask_b32_e32 v102, v102, v142, vcc
	v_cmp_le_i32_e32 vcc, v144, v126
	s_nop 1
	v_cndmask_b32_e32 v103, v199, v103, vcc
	v_cmp_le_i32_e32 vcc, v145, v126
	s_nop 1
	v_cndmask_b32_e32 v104, v199, v104, vcc
	v_cmp_le_i32_e32 vcc, v141, v126
	s_nop 1
	v_cndmask_b32_e32 v105, v199, v105, vcc
	v_cmp_gt_i32_e32 vcc, v143, v215
	s_nop 1
	v_cndmask_b32_e32 v86, v86, v142, vcc
	v_cmp_le_i32_e32 vcc, v144, v215
	s_nop 1
	v_cndmask_b32_e32 v87, v199, v87, vcc
	v_cmp_le_i32_e32 vcc, v145, v215
	s_nop 1
	v_cndmask_b32_e32 v88, v199, v88, vcc
	v_cmp_le_i32_e32 vcc, v141, v215
	s_nop 1
	v_cndmask_b32_e32 v89, v199, v89, vcc

; #define LAS __attribute__((address_space(3)))
; __device__ __forceinline__ void attn_prompt_unit(ArgsK& a, LAS unsigned char* lds, int b, int h, int qb, int tid, int wave, int lane) {
;     ...
;         if (more) { *(LAS u32x4*)(bufn + AT_K + skey * 144 + sch * 16) = kreg; *(LAS u32x4*)(bufn + AT_V + skey * 160 + sch * 16) = vreg; if (tid < 64) ((LAS float*)(bufn + AT_CK))[tid] = ckreg; }
;         kreg = kreg2; vreg = vreg2; ckreg = ckreg2;
.LBB0_270:
	s_add_i32 s18, s18, 1
	s_bitcmp1_b32 s18, 0
	s_cselect_b32 s14, 0x4d00, 0
	s_add_i32 s19, s14, 0
	v_add3_u32 v74, s19, v117, v207
	s_waitcnt vmcnt(5)
	ds_write_b128 v74, v[66:69]
	v_add3_u32 v66, s19, v208, v207
	s_waitcnt vmcnt(4)
	ds_write_b128 v66, v[70:73] offset:9216
	s_and_saveexec_b64 s[14:15], s[40:41]
	v_lshl_add_u32 v66, v160, 2, s19
	ds_write_b32 v66, v181 offset:19456
	s_or_b64 exec, exec, s[14:15]
	s_add_i32 s12, s12, 64
	v_lshl_add_u64 v[136:137], v[136:137], 0, s[26:27]
	s_cmp_lg_u32 s56, s18
	v_lshl_add_u64 v[138:139], v[138:139], 0, s[36:37]
	s_waitcnt lgkmcnt(0)
	s_barrier
	s_cbranch_scc0 .LBB0_274
	s_waitcnt vmcnt(3)
	v_mov_b64_e32 v[68:69], v[36:37]
	s_waitcnt vmcnt(2)
	v_mov_b64_e32 v[72:73], v[40:41]
	v_mov_b64_e32 v[66:67], v[34:35]
	v_mov_b64_e32 v[70:71], v[38:39]
	v_mul_f32_e32 v181, 0x3fb8aa3b, v180
	s_branch .LBB0_264

; #define LAS __attribute__((address_space(3)))
; #define MFMA16(a_, b_, c_) __builtin_amdgcn_mfma_f32_16x16x32_bf16((a_), (b_), (c_), 0, 0, 0)
; __device__ __forceinline__ void attn_prompt_unit(ArgsK& a, LAS unsigned char* lds, int b, int h, int qb, int tid, int wave, int lane) {
;     ...
;         if (kt * 64 <= qw + 31) {
;             const LAS float* CK = (const LAS float*)(bufc + AT_CK);
;             f32x4 st[4][2];
; #pragma unroll
;             for (int kb = 0; kb < 4; ++kb) { const bf16x8 k0 = *(const LAS bf16x8*)(bufc + AT_K + (kb * 16 + l15) * 144 + quad * 16), k1 = *(const LAS bf16x8*)(bufc + AT_K + (kb * 16 + l15) * 144 + 64 + quad * 16);
;                 const f32x4 ckv = *(const LAS f32x4*)(CK + kb * 16 + quad * 4);
; #pragma unroll
;                 for (int qq = 0; qq < 2; ++qq) { const f32x4 ci = (f32x4){cq[qq] - ckv[0], cq[qq] - ckv[1], cq[qq] - ckv[2], cq[qq] - ckv[3]};
;                     st[kb][qq] = MFMA16(k0, qf[qq][0], ci); st[kb][qq] = MFMA16(k1, qf[qq][1], st[kb][qq]); } }
;             if (kt * 64 + 63 > qw) {
; #pragma unroll
;                 for (int kb = 0; kb < 4; ++kb)
; #pragma unroll
;                     for (int qq = 0; qq < 2; ++qq)
; #pragma unroll
;                         for (int j = 0; j < 4; ++j) if (kt * 64 + kb * 16 + quad * 4 + j > qw + qq * 16 + l15) st[kb][qq][j] = -INFINITY; }
;     ...
;         if (more) { *(LAS u32x4*)(bufn + AT_K + skey * 144 + sch * 16) = kreg; *(LAS u32x4*)(bufn + AT_V + skey * 160 + sch * 16) = vreg; if (tid < 64) ((LAS float*)(bufn + AT_CK))[tid] = ckreg; }
;         kreg = kreg2; vreg = vreg2; ckreg = ckreg2;
;         __syncthreads();
.LBB0_278:
	s_waitcnt vmcnt(3)
	ds_write_b128 v217, v[34:37]
	s_waitcnt vmcnt(2)
	ds_write_b128 v218, v[38:41] offset:9216
	s_and_saveexec_b64 s[14:15], s[40:41]
	v_mul_f32_e32 v180, 0x3fb8aa3b, v180
	ds_write_b32 v216, v180 offset:19456
	s_or_b64 exec, exec, s[14:15]
	s_andn2_b64 vcc, exec, s[16:17]
	s_waitcnt lgkmcnt(0)
	s_barrier
	s_cbranch_vccnz .LBB0_236
	v_readlane_b32 s12, v253, 61
	s_andn2_b64 vcc, exec, s[42:43]
	s_nop 0
	v_add_u32_e32 v90, s12, v111
	ds_read_b128 v[34:37], v90 offset:19456
	ds_read_b128 v[38:41], v219
	ds_read_b128 v[66:69], v219 offset:64
	ds_read_b128 v[78:81], v90 offset:19520
	ds_read_b128 v[82:85], v219 offset:2304
	s_waitcnt lgkmcnt(4)
	v_sub_f32_e32 v73, v25, v37
	v_sub_f32_e32 v72, v24, v36
	v_sub_f32_e32 v71, v23, v35
	v_sub_f32_e32 v70, v20, v34
	v_sub_f32_e32 v37, v21, v37
	v_sub_f32_e32 v36, v22, v36
	v_sub_f32_e32 v35, v19, v35
	v_sub_f32_e32 v34, v18, v34
	s_waitcnt lgkmcnt(3)
	v_mfma_f32_16x16x32_bf16 v[70:73], v[38:41], v[6:9], v[70:73]
	v_mfma_f32_16x16x32_bf16 v[34:37], v[38:41], v[14:17], v[34:37]
	s_waitcnt lgkmcnt(2)
	v_mfma_f32_16x16x32_bf16 v[38:41], v[66:69], v[10:13], v[34:37]
	v_mfma_f32_16x16x32_bf16 v[70:73], v[66:69], v[2:5], v[70:73]
	s_nop 4
	ds_read_b128 v[34:37], v219 offset:2368
	s_waitcnt lgkmcnt(2)
	v_sub_f32_e32 v69, v25, v81
	v_sub_f32_e32 v68, v24, v80
	v_sub_f32_e32 v67, v23, v79
	v_sub_f32_e32 v66, v20, v78
	s_waitcnt lgkmcnt(1)
	s_nop 0
	v_mfma_f32_16x16x32_bf16 v[66:69], v[82:85], v[6:9], v[66:69]
	s_waitcnt lgkmcnt(0)
	v_mfma_f32_16x16x32_bf16 v[74:77], v[34:37], v[2:5], v[66:69]
	s_nop 5
	v_sub_f32_e32 v69, v21, v81
	v_sub_f32_e32 v68, v22, v80
	v_sub_f32_e32 v67, v19, v79
	v_sub_f32_e32 v66, v18, v78
	s_nop 1
	v_mfma_f32_16x16x32_bf16 v[66:69], v[82:85], v[14:17], v[66:69]
	ds_read_b128 v[82:85], v219 offset:4608
	ds_read_b128 v[86:89], v90 offset:19584
	s_waitcnt lgkmcnt(0)
	v_sub_f32_e32 v81, v25, v89
	v_sub_f32_e32 v80, v24, v88
	v_sub_f32_e32 v79, v23, v87
	v_sub_f32_e32 v78, v20, v86
	v_sub_f32_e32 v89, v21, v89
	v_sub_f32_e32 v88, v22, v88
	v_sub_f32_e32 v87, v19, v87
	v_sub_f32_e32 v86, v18, v86
	v_mfma_f32_16x16x32_bf16 v[34:37], v[34:37], v[10:13], v[66:69]
	s_nop 2
	ds_read_b128 v[66:69], v219 offset:4672
	ds_read_b128 v[90:93], v90 offset:19648
	s_waitcnt lgkmcnt(0)
	v_sub_f32_e32 v97, v25, v93
	v_mfma_f32_16x16x32_bf16 v[78:81], v[82:85], v[6:9], v[78:81]
	v_sub_f32_e32 v96, v24, v92
	v_sub_f32_e32 v95, v23, v91
	v_sub_f32_e32 v94, v20, v90
	v_mfma_f32_16x16x32_bf16 v[82:85], v[82:85], v[14:17], v[86:89]
	s_nop 2
	ds_read_b128 v[86:89], v220
	v_mfma_f32_16x16x32_bf16 v[78:81], v[66:69], v[2:5], v[78:81]
	v_mfma_f32_16x16x32_bf16 v[66:69], v[66:69], v[10:13], v[82:85]
	s_nop 2
	ds_read_b128 v[82:85], v220 offset:64
	s_waitcnt lgkmcnt(1)
	v_mfma_f32_16x16x32_bf16 v[6:9], v[86:89], v[6:9], v[94:97]
	s_waitcnt lgkmcnt(0)
	v_mfma_f32_16x16x32_bf16 v[2:5], v[82:85], v[2:5], v[6:9]
	s_nop 5
	v_sub_f32_e32 v9, v21, v93
	v_sub_f32_e32 v8, v22, v92
	v_sub_f32_e32 v7, v19, v91
	v_sub_f32_e32 v6, v18, v90
	s_nop 1
	v_mfma_f32_16x16x32_bf16 v[6:9], v[86:89], v[14:17], v[6:9]
	v_mfma_f32_16x16x32_bf16 v[10:13], v[82:85], v[10:13], v[6:9]
	s_cbranch_vccnz .LBB0_235
	v_readlane_b32 s14, v254, 57
	v_readlane_b32 s15, v254, 58
	s_nop 3
	v_mov_b32_e32 v6, s31
	v_cndmask_b32_e64 v6, v70, v6, s[44:45]
	v_cndmask_b32_e64 v72, v72, v199, s[14:15]
	v_readlane_b32 s14, v254, 59
	v_readlane_b32 s15, v254, 60
	v_cndmask_b32_e64 v70, v6, v70, s[46:47]
	v_mov_b32_e32 v6, s31
	v_cndmask_b32_e64 v73, v73, v199, s[14:15]
	v_readlane_b32 s14, v254, 61
	v_readlane_b32 s15, v254, 62
	v_cndmask_b32_e64 v71, v199, v71, s[46:47]
	v_cndmask_b32_e64 v39, v199, v39, s[54:55]
	v_cndmask_b32_e64 v6, v38, v6, s[14:15]
	v_readlane_b32 s14, v254, 63
	v_readlane_b32 s15, v252, 0
	v_cndmask_b32_e64 v38, v6, v38, s[54:55]
	v_mov_b32_e32 v6, s31
	v_cndmask_b32_e64 v40, v40, v199, s[14:15]
	v_readlane_b32 s14, v252, 1
	v_readlane_b32 s15, v252, 2
	v_cndmask_b32_e64 v34, v34, v6, s[44:45]
	v_cndmask_b32_e64 v35, v35, v199, s[68:69]
	v_cndmask_b32_e64 v41, v41, v199, s[14:15]
	v_readlane_b32 s14, v252, 3
	v_readlane_b32 s15, v252, 4
	v_cndmask_b32_e64 v36, v36, v199, s[70:71]
	v_cndmask_b32_e64 v37, v37, v199, s[72:73]
	v_cndmask_b32_e64 v74, v74, v6, s[14:15]
	v_readlane_b32 s14, v252, 5
	v_readlane_b32 s15, v252, 6
	v_cndmask_b32_e64 v78, v78, v6, s[74:75]
	v_cndmask_b32_e64 v79, v79, v199, s[76:77]
	v_cndmask_b32_e64 v75, v75, v199, s[14:15]
	v_readlane_b32 s14, v252, 7
	v_readlane_b32 s15, v252, 8
	v_cndmask_b32_e64 v80, v80, v199, s[78:79]
	v_cndmask_b32_e64 v81, v81, v199, s[80:81]
	v_cndmask_b32_e64 v76, v76, v199, s[14:15]
	v_readlane_b32 s14, v252, 9
	v_readlane_b32 s15, v252, 10
	v_cndmask_b32_e64 v66, v66, v6, s[82:83]
	v_cndmask_b32_e64 v67, v67, v199, s[84:85]
	v_cndmask_b32_e64 v77, v77, v199, s[14:15]
	v_cndmask_b32_e64 v68, v68, v199, s[86:87]
	v_cndmask_b32_e64 v69, v69, v199, s[88:89]
	v_cndmask_b32_e64 v2, v2, v6, s[90:91]
	v_cndmask_b32_e64 v3, v3, v199, s[92:93]
	v_cndmask_b32_e64 v4, v4, v199, s[94:95]
	v_cndmask_b32_e64 v5, v5, v199, s[96:97]
	v_cndmask_b32_e64 v10, v10, v6, s[4:5]
	v_cndmask_b32_e64 v11, v11, v199, s[6:7]
	v_cndmask_b32_e64 v12, v12, v199, s[8:9]
	v_cndmask_b32_e64 v13, v13, v199, s[10:11]
	s_branch .LBB0_235

; #define LAS __attribute__((address_space(3)))
; __device__ __forceinline__ void attn_sample_unit(ArgsK& a, LAS unsigned char* lds, int b, int h, int tid, int wave, int lane) {
;     const int l15 = lane & 15, quad = lane >> 4;
;     const bf16_t* QB = (const bf16_t*)(a.ws + WS_QB); const bf16_t* KB = (const bf16_t*)(a.ws + WS_KB); const bf16_t* VB = (const bf16_t*)(a.ws + WS_VB);
;     const float* CUM = (const float*)(a.ws + WS_CUMS) + ((size_t)b * CTOT) * 8 + h; bf16_t* MIX = (bf16_t*)(a.ws + WS_MIX);
;     const size_t rs = (size_t)MP + b * DSEQ;
;     const float* ckb = a.in[2] + ((size_t)b * PASTL) * 512 + h * 64; const float* cvb = a.in[3] + ((size_t)b * PASTL) * 512 + h * 64;
;     bf16x8 qf[2];
; #pragma unroll
;     for (int ks = 0; ks < 2; ++ks) qf[ks] = *(const bf16x8*)(QB + (rs + l15) * 512 + h * 64 + ks * 32 + quad * 8);
;     const float cq = CUM[(size_t)(PASTL + l15) * 8] * LOG2E;
;     f32x4 o[4]; float mrun = -INFINITY, lrun = 0.f;
; #pragma unroll
;     for (int d = 0; d < 4; ++d) o[d] = (f32x4){0.f, 0.f, 0.f, 0.f};
;     const int nch = (wave == 0) ? 9 : 8;
;     for (int ch = 0; ch < nch; ++ch) {
;         const bool nw = (ch == 8); const int k0 = wave * 256 + ch * 32;
;         f32x4 st[2];
;         if (!nw) {
; #pragma unroll
;             for (int kb = 0; kb < 2; ++kb) { const float* kp = ckb + (size_t)(k0 + kb * 16 + l15) * 512 + quad * 8;
;                 st[kb] = MFMA16(ld8f(kp), qf[0], ((f32x4){0.f, 0.f, 0.f, 0.f})); st[kb] = MFMA16(ld8f(kp + 32), qf[1], st[kb]);
; #pragma unroll
;                 for (int j = 0; j < 4; ++j) st[kb][j] += cq - CUM[(size_t)(k0 + kb * 16 + quad * 4 + j) * 8] * LOG2E; }
;         } else {
;             const bf16_t* kp = KB + (rs + l15) * 512 + h * 64 + quad * 8;
;             st[0] = MFMA16(*(const bf16x8*)kp, qf[0], ((f32x4){0.f, 0.f, 0.f, 0.f})); st[0] = MFMA16(*(const bf16x8*)(kp + 32), qf[1], st[0]);
; #pragma unroll
;             for (int j = 0; j < 4; ++j) { float sv = st[0][j] + (cq - CUM[(size_t)(PASTL + quad * 4 + j) * 8] * LOG2E); if (quad * 4 + j > l15) sv = -INFINITY; st[0][j] = sv; st[1][j] = -INFINITY; }
;         }
;         float mx = fmaxf(fmaxf(fmaxf(st[0][0], st[0][1]), fmaxf(st[0][2], st[0][3])), fmaxf(fmaxf(st[1][0], st[1][1]), fmaxf(st[1][2], st[1][3])));
;         mx = fmaxf(mx, __shfl_xor(mx, 16)); mx = fmaxf(mx, __shfl_xor(mx, 32));
.LBB0_286:
	s_ashr_i32 s14, s35, 3
	s_lshl_b32 s12, s14, 4
	s_and_b32 s24, s35, 7
	s_ashr_i32 s15, s14, 31
	s_ashr_i32 s17, s12, 31
	s_add_u32 s16, s12, 0x10000
	s_addc_u32 s17, s17, 0
	s_lshl_b32 s48, s24, 6
	s_lshl_b64 s[18:19], s[14:15], 22
	s_waitcnt lgkmcnt(0)
	s_add_u32 s43, s46, s18
	s_mul_i32 s42, s14, 0x10200
	s_addc_u32 s52, s47, s19
	s_lshl_b32 s12, s24, 7
	s_mul_hi_i32 s25, s14, 0x10200
	s_add_u32 s14, s28, s42
	s_addc_u32 s15, s29, s25
	s_lshl_b32 s25, s24, 2
	s_add_u32 s14, s14, s25
	s_addc_u32 s15, s15, 0
	v_mov_b32_e32 v37, v1
	v_lshl_add_u64 v[2:3], s[14:15], 0, v[36:37]
	s_mov_b32 s25, 0x10000
	v_add_co_u32_e32 v2, vcc, s25, v2
	v_lshlrev_b32_e32 v24, 1, v108
	s_nop 0
	v_addc_co_u32_e32 v3, vcc, 0, v3, vcc
	global_load_dword v58, v[2:3], off
	v_mov_b32_e32 v3, s17
	v_or_b32_e32 v2, s16, v106
	v_lshlrev_b64 v[22:23], 10, v[2:3]
	v_lshl_add_u64 v[2:3], s[54:55], 0, v[22:23]
	v_lshl_add_u64 v[2:3], v[2:3], 0, s[12:13]
	v_mov_b32_e32 v25, v1
	v_lshl_add_u64 v[6:7], v[2:3], 0, v[24:25]
	global_load_dwordx4 v[2:5], v[6:7], off
	s_nop 0
	global_load_dwordx4 v[6:9], v[6:7], off offset:64
	v_mov_b32_e32 v39, v1
	s_add_u32 s25, s44, s18
	v_or_b32_e32 v40, s16, v110
	v_mov_b32_e32 v41, s17
	v_lshl_add_u64 v[42:43], s[14:15], 0, v[38:39]
	s_addc_u32 s42, s45, s19
	s_lshl_b32 s24, s24, 8
	s_mov_b64 s[18:19], 0x10020
	v_lshlrev_b64 v[56:57], 10, v[40:41]
	v_lshl_add_u64 v[40:41], v[42:43], 0, s[36:37]
	v_lshl_add_u64 v[42:43], v[42:43], 0, s[18:19]
	s_add_u32 s18, s25, s24
	s_addc_u32 s19, s42, 0
	s_add_u32 s24, s43, s24
	v_lshlrev_b32_e32 v26, 2, v108
	v_mov_b32_e32 v27, v1
	s_addc_u32 s25, s52, 0
	v_lshl_add_u64 v[48:49], s[18:19], 0, v[26:27]
	s_add_u32 s18, s2, s12
	s_addc_u32 s19, s3, 0
	v_lshl_add_u64 v[22:23], s[18:19], 0, v[22:23]
	s_add_u32 s18, s0, s12
	s_addc_u32 s19, s1, 0
	v_lshlrev_b32_e32 v28, 2, v106
	v_mov_b32_e32 v29, v1
	v_lshlrev_b32_e32 v54, 1, v106
	v_mov_b32_e32 v55, v1
	v_mov_b32_e32 v37, 0
	v_lshl_add_u64 v[44:45], v[30:31], 2, s[14:15]
	v_lshl_add_u64 v[46:47], v[32:33], 2, s[14:15]
	v_lshl_add_u64 v[52:53], v[22:23], 0, v[24:25]
	v_lshl_add_u64 v[22:23], s[18:19], 0, v[56:57]
	s_mov_b32 s49, 0
	v_mov_b32_e32 v86, 0xff800000
	v_mov_b32_e32 v10, 0
	v_mov_b32_e32 v14, 0
	v_mov_b32_e32 v18, 0
	v_mov_b32_e32 v11, v37
	v_mov_b32_e32 v12, v37
	v_mov_b32_e32 v13, v37
	v_mov_b32_e32 v15, v37
	v_mov_b32_e32 v16, v37
	v_mov_b32_e32 v17, v37
	v_mov_b32_e32 v19, v37
	v_mov_b32_e32 v20, v37
	v_mov_b32_e32 v21, v37
	v_lshl_add_u64 v[44:45], v[44:45], 0, s[36:37]
	v_lshl_add_u64 v[46:47], v[46:47], 0, s[36:37]
	v_lshl_add_u64 v[50:51], s[24:25], 0, v[28:29]
	v_lshl_add_u64 v[54:55], v[22:23], 0, v[54:55]
	v_mov_b32_e32 v22, 0
	v_mov_b32_e32 v23, v37
	v_mov_b32_e32 v24, v37
	v_mov_b32_e32 v25, v37
	s_waitcnt vmcnt(2)
	v_mul_f32_e32 v56, 0x3fb8aa3b, v58
	v_mov_b32_e32 v57, v56
	v_mov_b32_e32 v58, v56
	v_mov_b32_e32 v59, v56
	v_mov_b32_e32 v60, v56
	v_mov_b32_e32 v61, v56
	v_mov_b32_e32 v62, v56
	v_mov_b32_e32 v63, v56
	v_mov_b32_e32 v64, v56
	v_mov_b32_e32 v65, v56
	s_mov_b64 s[58:59], 0x8000
	s_mov_b64 s[72:73], 0x1000
	s_mov_b32 s53, 0
	v_add_u32_e32 v250, s53, v77
	v_ashrrev_i32_e32 v251, 31, v250
	v_lshlrev_b64 v[250:251], 11, v[250:251]
	v_lshl_add_u64 v[90:91], v[48:49], 0, v[250:251]
	v_lshl_add_u64 v[92:93], v[90:91], 0, s[58:59]
	global_load_dwordx4 v[112:115], v[90:91], off nt
	global_load_dwordx4 v[116:119], v[90:91], off offset:16 nt
	global_load_dwordx4 v[120:123], v[90:91], off offset:128 nt
	global_load_dwordx4 v[124:127], v[90:91], off offset:144 nt
	global_load_dwordx4 v[128:131], v[92:93], off nt
	global_load_dwordx4 v[132:135], v[92:93], off offset:16 nt
	global_load_dwordx4 v[136:139], v[92:93], off offset:128 nt
	global_load_dwordx4 v[140:143], v[92:93], off offset:144 nt
	v_add_u32_e32 v250, s53, v76
	v_ashrrev_i32_e32 v251, 31, v250
	v_lshlrev_b64 v[250:251], 5, v[250:251]
	v_lshl_add_u64 v[94:95], s[14:15], 0, v[250:251]
	global_load_dword v238, v[94:95], off
	global_load_dword v239, v[94:95], off offset:32
	global_load_dword v240, v[94:95], off offset:64
	global_load_dword v241, v[94:95], off offset:96
	global_load_dword v242, v[94:95], off offset:512
	global_load_dword v243, v[94:95], off offset:544
	global_load_dword v244, v[94:95], off offset:576
	global_load_dword v245, v[94:95], off offset:608
	v_add_u32_e32 v250, s53, v76
	v_ashrrev_i32_e32 v251, 31, v250
	v_lshlrev_b64 v[250:251], 11, v[250:251]
	v_lshl_add_u64 v[96:97], v[50:51], 0, v[250:251]
	v_lshl_add_u64 v[98:99], v[96:97], 0, s[72:73]
	v_lshl_add_u64 v[100:101], v[96:97], 0, s[58:59]
	v_lshl_add_u64 v[102:103], v[98:99], 0, s[58:59]
	global_load_dword v206, v[96:97], off nt
	global_load_dword v207, v[96:97], off offset:2048 nt
	global_load_dword v208, v[98:99], off nt
	global_load_dword v209, v[98:99], off offset:2048 nt
	global_load_dword v210, v[100:101], off nt
	global_load_dword v211, v[100:101], off offset:2048 nt
	global_load_dword v212, v[102:103], off nt
	global_load_dword v213, v[102:103], off offset:2048 nt
	global_load_dword v214, v[96:97], off offset:64 nt
	global_load_dword v215, v[96:97], off offset:2112 nt
	global_load_dword v216, v[98:99], off offset:64 nt
	global_load_dword v217, v[98:99], off offset:2112 nt
	global_load_dword v218, v[100:101], off offset:64 nt
	global_load_dword v219, v[100:101], off offset:2112 nt
	global_load_dword v220, v[102:103], off offset:64 nt
	global_load_dword v221, v[102:103], off offset:2112 nt
	global_load_dword v222, v[96:97], off offset:128 nt
	global_load_dword v223, v[96:97], off offset:2176 nt
	global_load_dword v224, v[98:99], off offset:128 nt
	global_load_dword v225, v[98:99], off offset:2176 nt
	global_load_dword v226, v[100:101], off offset:128 nt
	global_load_dword v227, v[100:101], off offset:2176 nt
	global_load_dword v228, v[102:103], off offset:128 nt
	global_load_dword v229, v[102:103], off offset:2176 nt
	global_load_dword v230, v[96:97], off offset:192 nt
	global_load_dword v231, v[96:97], off offset:2240 nt
	global_load_dword v232, v[98:99], off offset:192 nt
	global_load_dword v233, v[98:99], off offset:2240 nt
	global_load_dword v234, v[100:101], off offset:192 nt
	global_load_dword v235, v[100:101], off offset:2240 nt
	global_load_dword v236, v[102:103], off offset:192 nt
	global_load_dword v237, v[102:103], off offset:2240 nt
; #define MFMA16(a_, b_, c_) __builtin_amdgcn_mfma_f32_16x16x32_bf16((a_), (b_), (c_), 0, 0, 0)
; __device__ __forceinline__ bf16x8 pack8(const f32x4& lo, const f32x4& hi) { u32x4 w; w.x = cvt_pk_bf16(lo[0], lo[1]); w.y = cvt_pk_bf16(lo[2], lo[3]); w.z = cvt_pk_bf16(hi[0], hi[1]); w.w = cvt_pk_bf16(hi[2], hi[3]); return __builtin_bit_cast(bf16x8, w); }
; __device__ __forceinline__ bf16x8 ld8f(const float* p) { const f32x4 x = __builtin_nontemporal_load((const f32x4*)p), y = __builtin_nontemporal_load((const f32x4*)(p + 4)); return pack8(x, y); }
; __device__ __forceinline__ void attn_sample_unit(ArgsK& a, LAS unsigned char* lds, int b, int h, int tid, int wave, int lane) {
;     ...
;     for (int ch = 0; ch < nch; ++ch) {
;         const bool nw = (ch == 8); const int k0 = wave * 256 + ch * 32;
;         f32x4 st[2];
;         if (!nw) {
; #pragma unroll
;             for (int kb = 0; kb < 2; ++kb) { const float* kp = ckb + (size_t)(k0 + kb * 16 + l15) * 512 + quad * 8;
;                 st[kb] = MFMA16(ld8f(kp), qf[0], ((f32x4){0.f, 0.f, 0.f, 0.f})); st[kb] = MFMA16(ld8f(kp + 32), qf[1], st[kb]);
; #pragma unroll
;                 for (int j = 0; j < 4; ++j) st[kb][j] += cq - CUM[(size_t)(k0 + kb * 16 + quad * 4 + j) * 8] * LOG2E; }
;         } else {
;             const bf16_t* kp = KB + (rs + l15) * 512 + h * 64 + quad * 8;
;             st[0] = MFMA16(*(const bf16x8*)kp, qf[0], ((f32x4){0.f, 0.f, 0.f, 0.f})); st[0] = MFMA16(*(const bf16x8*)(kp + 32), qf[1], st[0]);
; #pragma unroll
;             for (int j = 0; j < 4; ++j) { float sv = st[0][j] + (cq - CUM[(size_t)(PASTL + quad * 4 + j) * 8] * LOG2E); if (quad * 4 + j > l15) sv = -INFINITY; st[0][j] = sv; st[1][j] = -INFINITY; }
;         }
;         float mx = fmaxf(fmaxf(fmaxf(st[0][0], st[0][1]), fmaxf(st[0][2], st[0][3])), fmaxf(fmaxf(st[1][0], st[1][1]), fmaxf(st[1][2], st[1][3])));
;         mx = fmaxf(mx, __shfl_xor(mx, 16)); mx = fmaxf(mx, __shfl_xor(mx, 32));
;         const float mnew = fmaxf(mrun, mx), alpha = __builtin_amdgcn_exp2f(mrun - mnew); mrun = mnew; float ps = 0.f;
; #pragma unroll
;         for (int kb = 0; kb < 2; ++kb)
; #pragma unroll
;             for (int j = 0; j < 4; ++j) { const float p = __builtin_amdgcn_exp2f(st[kb][j] - mnew); st[kb][j] = p; ps += p; }
;         lrun = lrun * alpha + ps;
;         const bf16x8 pf = pack8(st[0], st[1]);
.Lsatt_loop:
	s_add_i32 s53, s49, 32
	s_min_i32 s53, s53, 0xe0
	s_waitcnt vmcnt(40)
	v_cvt_pk_bf16_f32 v170, v112, v113
	v_cvt_pk_bf16_f32 v171, v114, v115
	v_cvt_pk_bf16_f32 v172, v116, v117
	v_cvt_pk_bf16_f32 v173, v118, v119
	v_cvt_pk_bf16_f32 v174, v120, v121
	v_cvt_pk_bf16_f32 v175, v122, v123
	v_cvt_pk_bf16_f32 v176, v124, v125
	v_cvt_pk_bf16_f32 v177, v126, v127
	s_nop 1
	v_mfma_f32_16x16x32_bf16 v[162:165], v[170:173], v[2:5], 0
	v_mfma_f32_16x16x32_bf16 v[162:165], v[174:177], v[6:9], v[162:165]
	v_cvt_pk_bf16_f32 v170, v128, v129
	v_cvt_pk_bf16_f32 v171, v130, v131
	v_cvt_pk_bf16_f32 v172, v132, v133
	v_cvt_pk_bf16_f32 v173, v134, v135
	v_cvt_pk_bf16_f32 v174, v136, v137
	v_cvt_pk_bf16_f32 v175, v138, v139
	v_cvt_pk_bf16_f32 v176, v140, v141
	v_cvt_pk_bf16_f32 v177, v142, v143
	s_nop 1
	v_mfma_f32_16x16x32_bf16 v[166:169], v[170:173], v[2:5], 0
	v_mfma_f32_16x16x32_bf16 v[166:169], v[174:177], v[6:9], v[166:169]
	v_add_u32_e32 v250, s53, v77
	v_ashrrev_i32_e32 v251, 31, v250
	v_lshlrev_b64 v[250:251], 11, v[250:251]
	v_lshl_add_u64 v[90:91], v[48:49], 0, v[250:251]
	v_lshl_add_u64 v[92:93], v[90:91], 0, s[58:59]
	global_load_dwordx4 v[112:115], v[90:91], off nt
	global_load_dwordx4 v[116:119], v[90:91], off offset:16 nt
	global_load_dwordx4 v[120:123], v[90:91], off offset:128 nt
	global_load_dwordx4 v[124:127], v[90:91], off offset:144 nt
	global_load_dwordx4 v[128:131], v[92:93], off nt
	global_load_dwordx4 v[132:135], v[92:93], off offset:16 nt
	global_load_dwordx4 v[136:139], v[92:93], off offset:128 nt
	global_load_dwordx4 v[140:143], v[92:93], off offset:144 nt
	s_waitcnt vmcnt(40)
	v_fma_f32 v238, v238, s76, v56
	v_fma_f32 v239, v239, s76, v56
	v_fma_f32 v240, v240, s76, v56
	v_fma_f32 v241, v241, s76, v56
	v_fma_f32 v242, v242, s76, v56
	v_fma_f32 v243, v243, s76, v56
	v_fma_f32 v244, v244, s76, v56
	v_fma_f32 v245, v245, s76, v56
	v_add_f32_e32 v162, v162, v238
	v_add_f32_e32 v163, v163, v239
	v_add_f32_e32 v164, v164, v240
	v_add_f32_e32 v165, v165, v241
	v_add_f32_e32 v166, v166, v242
	v_add_f32_e32 v167, v167, v243
	v_add_f32_e32 v168, v168, v244
	v_add_f32_e32 v169, v169, v245
	v_add_u32_e32 v250, s53, v76
	v_ashrrev_i32_e32 v251, 31, v250
	v_lshlrev_b64 v[250:251], 5, v[250:251]
	v_lshl_add_u64 v[94:95], s[14:15], 0, v[250:251]
	global_load_dword v238, v[94:95], off
	global_load_dword v239, v[94:95], off offset:32
	global_load_dword v240, v[94:95], off offset:64
	global_load_dword v241, v[94:95], off offset:96
	global_load_dword v242, v[94:95], off offset:512
	global_load_dword v243, v[94:95], off offset:544
	global_load_dword v244, v[94:95], off offset:576
	global_load_dword v245, v[94:95], off offset:608
	v_max_f32_e32 v186, v162, v163
	v_max_f32_e32 v187, v164, v165
	v_max_f32_e32 v186, v186, v187
	v_max_f32_e32 v187, v166, v167
	v_max_f32_e32 v161, v168, v169
	v_max_f32_e32 v187, v187, v161
	v_max_f32_e32 v186, v186, v187
	v_mov_b32_e32 v187, v186
	s_nop 1
	v_permlane16_swap_b32_e32 v186, v187
	v_max_f32_e32 v186, v186, v187
	v_mov_b32_e32 v187, v186
	s_nop 1
	v_permlane32_swap_b32_e32 v186, v187
	v_max3_f32 v188, v86, v186, v187
	v_sub_f32_e32 v190, v86, v188
	v_exp_f32_e32 v190, v190
	v_sub_f32_e32 v162, v162, v188
	v_sub_f32_e32 v163, v163, v188
	v_sub_f32_e32 v164, v164, v188
	v_sub_f32_e32 v165, v165, v188
	v_sub_f32_e32 v166, v166, v188
	v_sub_f32_e32 v167, v167, v188
	v_sub_f32_e32 v168, v168, v188
	v_sub_f32_e32 v169, v169, v188
	v_exp_f32_e32 v162, v162
	v_exp_f32_e32 v163, v163
	v_exp_f32_e32 v164, v164
	v_exp_f32_e32 v165, v165
	v_exp_f32_e32 v166, v166
	v_exp_f32_e32 v167, v167
	v_exp_f32_e32 v168, v168
	v_exp_f32_e32 v169, v169
	v_mov_b32_e32 v86, v188
	v_mov_b32_e32 v39, v188
	v_mov_b32_e32 v191, v190
	v_add_f32_e32 v189, 0, v162
	v_add_f32_e32 v189, v189, v163
	v_add_f32_e32 v189, v189, v164
	v_add_f32_e32 v189, v189, v165
	v_add_f32_e32 v189, v189, v166
	v_add_f32_e32 v189, v189, v167
	v_add_f32_e32 v189, v189, v168
	v_add_f32_e32 v189, v189, v169
	v_fmac_f32_e32 v189, v37, v190
	v_mov_b32_e32 v37, v189
	v_mov_b32_e32 v26, v189
	v_cvt_pk_bf16_f32 v178, v162, v163
	v_cvt_pk_bf16_f32 v179, v164, v165
	v_cvt_pk_bf16_f32 v180, v166, v167
	v_cvt_pk_bf16_f32 v181, v168, v169
	v_pk_mul_f32 v[22:23], v[22:23], v[190:191]
	v_pk_mul_f32 v[24:25], v[24:25], v[190:191]
	v_pk_mul_f32 v[18:19], v[18:19], v[190:191]
	v_pk_mul_f32 v[20:21], v[20:21], v[190:191]
	v_pk_mul_f32 v[14:15], v[14:15], v[190:191]
	v_pk_mul_f32 v[16:17], v[16:17], v[190:191]
	v_pk_mul_f32 v[10:11], v[10:11], v[190:191]
	v_pk_mul_f32 v[12:13], v[12:13], v[190:191]
	s_waitcnt vmcnt(40)
; __device__ __forceinline__ float bf2f(unsigned short b) { return __uint_as_float(((unsigned)b) << 16); }
; #define MFMA16(a_, b_, c_) __builtin_amdgcn_mfma_f32_16x16x32_bf16((a_), (b_), (c_), 0, 0, 0)
; __device__ __forceinline__ bf16x8 pack8(const f32x4& lo, const f32x4& hi) { u32x4 w; w.x = cvt_pk_bf16(lo[0], lo[1]); w.y = cvt_pk_bf16(lo[2], lo[3]); w.z = cvt_pk_bf16(hi[0], hi[1]); w.w = cvt_pk_bf16(hi[2], hi[3]); return __builtin_bit_cast(bf16x8, w); }
; __device__ __forceinline__ void attn_sample_unit(ArgsK& a, LAS unsigned char* lds, int b, int h, int tid, int wave, int lane) {
;     ...
; #pragma unroll
;         for (int d = 0; d < 4; ++d) { f32x4 lo, hi;
;             if (!nw) { const float* vp = cvb + (size_t)(k0 + quad * 4) * 512 + d * 16 + l15;
; #pragma unroll
;                 for (int j = 0; j < 4; ++j) { lo[j] = __builtin_nontemporal_load(vp + (size_t)j * 512); hi[j] = __builtin_nontemporal_load(vp + (size_t)(16 + j) * 512); } }
;             else { const bf16_t* vp = VB + (rs + quad * 4) * 512 + h * 64 + d * 16 + l15;
; #pragma unroll
;                 for (int j = 0; j < 4; ++j) { lo[j] = bf2f(vp[(size_t)j * 512]); hi[j] = 0.f; } }
;             o[d] = MFMA16(pack8(lo, hi), pf, o[d] * alpha); }
;     }
;     lrun += __shfl_xor(lrun, 16); lrun += __shfl_xor(lrun, 32);
	v_cvt_pk_bf16_f32 v182, v206, v207
	v_cvt_pk_bf16_f32 v183, v208, v209
	v_cvt_pk_bf16_f32 v184, v210, v211
	v_cvt_pk_bf16_f32 v185, v212, v213
	s_nop 1
	v_mfma_f32_16x16x32_bf16 v[22:25], v[182:185], v[178:181], v[22:25]
	s_waitcnt vmcnt(32)
	v_cvt_pk_bf16_f32 v246, v214, v215
	v_cvt_pk_bf16_f32 v247, v216, v217
	v_cvt_pk_bf16_f32 v248, v218, v219
	v_cvt_pk_bf16_f32 v249, v220, v221
	s_nop 1
	v_mfma_f32_16x16x32_bf16 v[18:21], v[246:249], v[178:181], v[18:21]
	s_waitcnt vmcnt(24)
	v_cvt_pk_bf16_f32 v182, v222, v223
	v_cvt_pk_bf16_f32 v183, v224, v225
	v_cvt_pk_bf16_f32 v184, v226, v227
	v_cvt_pk_bf16_f32 v185, v228, v229
	s_nop 1
	v_mfma_f32_16x16x32_bf16 v[14:17], v[182:185], v[178:181], v[14:17]
	s_waitcnt vmcnt(16)
	v_cvt_pk_bf16_f32 v246, v230, v231
	v_cvt_pk_bf16_f32 v247, v232, v233
	v_cvt_pk_bf16_f32 v248, v234, v235
	v_cvt_pk_bf16_f32 v249, v236, v237
	s_nop 1
	v_mfma_f32_16x16x32_bf16 v[10:13], v[246:249], v[178:181], v[10:13]
	v_add_u32_e32 v250, s53, v76
	v_ashrrev_i32_e32 v251, 31, v250
	v_lshlrev_b64 v[250:251], 11, v[250:251]
	v_lshl_add_u64 v[96:97], v[50:51], 0, v[250:251]
	v_lshl_add_u64 v[98:99], v[96:97], 0, s[72:73]
	v_lshl_add_u64 v[100:101], v[96:97], 0, s[58:59]
	v_lshl_add_u64 v[102:103], v[98:99], 0, s[58:59]
	global_load_dword v206, v[96:97], off nt
	global_load_dword v207, v[96:97], off offset:2048 nt
	global_load_dword v208, v[98:99], off nt
	global_load_dword v209, v[98:99], off offset:2048 nt
	global_load_dword v210, v[100:101], off nt
	global_load_dword v211, v[100:101], off offset:2048 nt
	global_load_dword v212, v[102:103], off nt
	global_load_dword v213, v[102:103], off offset:2048 nt
	global_load_dword v214, v[96:97], off offset:64 nt
	global_load_dword v215, v[96:97], off offset:2112 nt
	global_load_dword v216, v[98:99], off offset:64 nt
	global_load_dword v217, v[98:99], off offset:2112 nt
	global_load_dword v218, v[100:101], off offset:64 nt
	global_load_dword v219, v[100:101], off offset:2112 nt
	global_load_dword v220, v[102:103], off offset:64 nt
	global_load_dword v221, v[102:103], off offset:2112 nt
	global_load_dword v222, v[96:97], off offset:128 nt
	global_load_dword v223, v[96:97], off offset:2176 nt
	global_load_dword v224, v[98:99], off offset:128 nt
	global_load_dword v225, v[98:99], off offset:2176 nt
	global_load_dword v226, v[100:101], off offset:128 nt
	global_load_dword v227, v[100:101], off offset:2176 nt
	global_load_dword v228, v[102:103], off offset:128 nt
	global_load_dword v229, v[102:103], off offset:2176 nt
	global_load_dword v230, v[96:97], off offset:192 nt
	global_load_dword v231, v[96:97], off offset:2240 nt
	global_load_dword v232, v[98:99], off offset:192 nt
	global_load_dword v233, v[98:99], off offset:2240 nt
	global_load_dword v234, v[100:101], off offset:192 nt
	global_load_dword v235, v[100:101], off offset:2240 nt
	global_load_dword v236, v[102:103], off offset:192 nt
	global_load_dword v237, v[102:103], off offset:2240 nt
	s_add_i32 s49, s49, 32
	s_cmpk_lg_i32 s49, 0x100
	s_cbranch_scc1 .Lsatt_loop
	v_xor_b32_e32 v87, 16, v200
	v_xor_b32_e32 v88, 32, v200
	v_lshlrev_b32_e32 v87, 2, v87
	v_lshlrev_b32_e32 v88, 2, v88
	s_cmp_eq_u32 s34, s49
	s_cbranch_scc1 .LBB0_309
	s_waitcnt vmcnt(0)
